# GEMM K-loops: issue the four A-operand DMA pieces before the four weight-tile pieces (A comes from further away)
# speedup vs baseline: 1.0042x; 1.0042x over previous
.LBB0_203:
	ds_read_b128 v[226:229], v157
	ds_read_b128 v[230:233], v158
	ds_read_b128 v[234:237], v159
	s_waitcnt lgkmcnt(5)
	v_mfma_f32_16x16x32_bf16 v[124:127], v[214:217], v[174:177], v[124:127]
	v_mfma_f32_16x16x32_bf16 v[120:123], v[214:217], v[178:181], v[120:123]
	v_mfma_f32_16x16x32_bf16 v[116:119], v[214:217], v[182:185], v[116:119]
	v_mfma_f32_16x16x32_bf16 v[112:115], v[214:217], v[186:189], v[112:115]
	ds_read_b128 v[238:241], v160
	s_waitcnt lgkmcnt(5)
	v_mfma_f32_16x16x32_bf16 v[108:111], v[218:221], v[174:177], v[108:111]
	v_mfma_f32_16x16x32_bf16 v[104:107], v[218:221], v[178:181], v[104:107]
	v_mfma_f32_16x16x32_bf16 v[100:103], v[218:221], v[182:185], v[100:103]
	v_mfma_f32_16x16x32_bf16 v[96:99], v[218:221], v[186:189], v[96:99]
	ds_read_b128 v[242:245], v161
	ds_read_b128 v[190:193], v153 offset:33792
	s_waitcnt lgkmcnt(6)
	v_mfma_f32_16x16x32_bf16 v[92:95], v[222:225], v[174:177], v[92:95]
	v_mfma_f32_16x16x32_bf16 v[88:91], v[222:225], v[178:181], v[88:91]
	v_mfma_f32_16x16x32_bf16 v[84:87], v[222:225], v[182:185], v[84:87]
	v_mfma_f32_16x16x32_bf16 v[80:83], v[222:225], v[186:189], v[80:83]
	ds_read_b128 v[214:217], v154 offset:1024
	ds_read_b128 v[194:197], v153 offset:35840
	s_waitcnt lgkmcnt(7)
	v_mfma_f32_16x16x32_bf16 v[76:79], v[226:229], v[174:177], v[76:79]
	v_mfma_f32_16x16x32_bf16 v[72:75], v[226:229], v[178:181], v[72:75]
	v_mfma_f32_16x16x32_bf16 v[68:71], v[226:229], v[182:185], v[68:71]
	v_mfma_f32_16x16x32_bf16 v[64:67], v[226:229], v[186:189], v[64:67]
	ds_read_b128 v[218:221], v155 offset:1024
	ds_read_b128 v[198:201], v153 offset:37888
	s_waitcnt lgkmcnt(8)
	v_mfma_f32_16x16x32_bf16 v[60:63], v[230:233], v[174:177], v[60:63]
	v_mfma_f32_16x16x32_bf16 v[56:59], v[230:233], v[178:181], v[56:59]
	v_mfma_f32_16x16x32_bf16 v[52:55], v[230:233], v[182:185], v[52:55]
	v_mfma_f32_16x16x32_bf16 v[48:51], v[230:233], v[186:189], v[48:51]
	ds_read_b128 v[222:225], v156 offset:1024
	ds_read_b128 v[210:213], v153 offset:39936
	s_waitcnt lgkmcnt(9)
	v_mfma_f32_16x16x32_bf16 v[44:47], v[234:237], v[174:177], v[44:47]
	v_mfma_f32_16x16x32_bf16 v[40:43], v[234:237], v[178:181], v[40:43]
	v_mfma_f32_16x16x32_bf16 v[36:39], v[234:237], v[182:185], v[36:39]
	v_mfma_f32_16x16x32_bf16 v[32:35], v[234:237], v[186:189], v[32:35]
	ds_read_b128 v[226:229], v157 offset:1024
	s_waitcnt lgkmcnt(9)
	v_mfma_f32_16x16x32_bf16 v[28:31], v[238:241], v[174:177], v[28:31]
	v_mfma_f32_16x16x32_bf16 v[24:27], v[238:241], v[178:181], v[24:27]
	v_mfma_f32_16x16x32_bf16 v[20:23], v[238:241], v[182:185], v[20:23]
	v_mfma_f32_16x16x32_bf16 v[16:19], v[238:241], v[186:189], v[16:19]
	ds_read_b128 v[230:233], v158 offset:1024
	s_waitcnt lgkmcnt(9)
	v_mfma_f32_16x16x32_bf16 v[12:15], v[242:245], v[174:177], v[12:15]
	v_mfma_f32_16x16x32_bf16 v[8:11], v[242:245], v[178:181], v[8:11]
	v_mfma_f32_16x16x32_bf16 v[4:7], v[242:245], v[182:185], v[4:7]
	v_mfma_f32_16x16x32_bf16 v[0:3], v[242:245], v[186:189], v[0:3]
	ds_read_b128 v[234:237], v159 offset:1024
	s_waitcnt lgkmcnt(3)
	v_mfma_f32_16x16x32_bf16 v[124:127], v[214:217], v[190:193], v[124:127]
	v_mfma_f32_16x16x32_bf16 v[120:123], v[214:217], v[194:197], v[120:123]
	v_mfma_f32_16x16x32_bf16 v[116:119], v[214:217], v[198:201], v[116:119]
	v_mfma_f32_16x16x32_bf16 v[112:115], v[214:217], v[210:213], v[112:115]
	ds_read_b128 v[238:241], v160 offset:1024
	v_mfma_f32_16x16x32_bf16 v[108:111], v[218:221], v[190:193], v[108:111]
	v_mfma_f32_16x16x32_bf16 v[104:107], v[218:221], v[194:197], v[104:107]
	v_mfma_f32_16x16x32_bf16 v[100:103], v[218:221], v[198:201], v[100:103]
	v_mfma_f32_16x16x32_bf16 v[96:99], v[218:221], v[210:213], v[96:99]
	ds_read_b128 v[242:245], v161 offset:1024
	v_mfma_f32_16x16x32_bf16 v[92:95], v[222:225], v[190:193], v[92:95]
	v_mfma_f32_16x16x32_bf16 v[88:91], v[222:225], v[194:197], v[88:91]
	v_mfma_f32_16x16x32_bf16 v[84:87], v[222:225], v[198:201], v[84:87]
	v_mfma_f32_16x16x32_bf16 v[80:83], v[222:225], v[210:213], v[80:83]
	s_waitcnt lgkmcnt(4)
	v_mfma_f32_16x16x32_bf16 v[76:79], v[226:229], v[190:193], v[76:79]
	v_mfma_f32_16x16x32_bf16 v[72:75], v[226:229], v[194:197], v[72:75]
	v_mfma_f32_16x16x32_bf16 v[68:71], v[226:229], v[198:201], v[68:71]
	v_mfma_f32_16x16x32_bf16 v[64:67], v[226:229], v[210:213], v[64:67]
	s_waitcnt lgkmcnt(3)
	v_mfma_f32_16x16x32_bf16 v[60:63], v[230:233], v[190:193], v[60:63]
	v_mfma_f32_16x16x32_bf16 v[56:59], v[230:233], v[194:197], v[56:59]
	v_mfma_f32_16x16x32_bf16 v[52:55], v[230:233], v[198:201], v[52:55]
	v_mfma_f32_16x16x32_bf16 v[48:51], v[230:233], v[210:213], v[48:51]
	s_waitcnt lgkmcnt(0)
	s_waitcnt vmcnt(0)
	s_barrier
	ds_read_b128 v[174:177], v162 offset:32768
	ds_read_b128 v[178:181], v162 offset:34816
	ds_read_b128 v[182:185], v162 offset:36864
	ds_read_b128 v[186:189], v162 offset:38912
	ds_read_b128 v[214:217], v170
	ds_read_b128 v[218:221], v171
	ds_read_b128 v[222:225], v163
	s_cmp_gt_u32 s23, 13
	s_cbranch_scc1 .Lg1_nostage0
	s_add_u32 m0, s24, 0x0
	v_mfma_f32_16x16x32_bf16 v[44:47], v[234:237], v[190:193], v[44:47]
	global_load_lds_dwordx4 v246, s[98:99]
	s_add_u32 m0, s24, 0x2000
	v_mfma_f32_16x16x32_bf16 v[40:43], v[234:237], v[194:197], v[40:43]
	global_load_lds_dwordx4 v247, s[98:99]
	s_add_u32 m0, s24, 0x4000
	v_mfma_f32_16x16x32_bf16 v[36:39], v[234:237], v[198:201], v[36:39]
	global_load_lds_dwordx4 v248, s[98:99]
	s_add_u32 m0, s24, 0x6000
	v_mfma_f32_16x16x32_bf16 v[32:35], v[234:237], v[210:213], v[32:35]
	global_load_lds_dwordx4 v249, s[98:99]
	s_add_u32 m0, s24, 0x8000
	v_mfma_f32_16x16x32_bf16 v[28:31], v[238:241], v[190:193], v[28:31]
	global_load_lds_dwordx4 v246, s[100:101]
	s_add_u32 m0, s24, 0xa000
	v_mfma_f32_16x16x32_bf16 v[24:27], v[238:241], v[194:197], v[24:27]
	global_load_lds_dwordx4 v247, s[100:101]
	s_add_u32 m0, s24, 0xc000
	v_mfma_f32_16x16x32_bf16 v[20:23], v[238:241], v[198:201], v[20:23]
	global_load_lds_dwordx4 v248, s[100:101]
	s_add_u32 m0, s24, 0xe000
	v_mfma_f32_16x16x32_bf16 v[16:19], v[238:241], v[210:213], v[16:19]
	global_load_lds_dwordx4 v249, s[100:101]
	v_mfma_f32_16x16x32_bf16 v[12:15], v[242:245], v[190:193], v[12:15]
	v_mfma_f32_16x16x32_bf16 v[8:11], v[242:245], v[194:197], v[8:11]
	v_mfma_f32_16x16x32_bf16 v[4:7], v[242:245], v[198:201], v[4:7]
	v_mfma_f32_16x16x32_bf16 v[0:3], v[242:245], v[210:213], v[0:3]
	s_add_u32 s98, s98, 0x80
	s_addc_u32 s99, s99, 0
	s_add_u32 s100, s100, 0x80
	s_addc_u32 s101, s101, 0
	s_branch .Lg1_half1

.Lg1_half1:
	ds_read_b128 v[226:229], v164
	ds_read_b128 v[230:233], v165
	ds_read_b128 v[234:237], v166
	s_waitcnt lgkmcnt(5)
	v_mfma_f32_16x16x32_bf16 v[124:127], v[214:217], v[174:177], v[124:127]
	v_mfma_f32_16x16x32_bf16 v[120:123], v[214:217], v[178:181], v[120:123]
	v_mfma_f32_16x16x32_bf16 v[116:119], v[214:217], v[182:185], v[116:119]
	v_mfma_f32_16x16x32_bf16 v[112:115], v[214:217], v[186:189], v[112:115]
	ds_read_b128 v[238:241], v167
	s_waitcnt lgkmcnt(5)
	v_mfma_f32_16x16x32_bf16 v[108:111], v[218:221], v[174:177], v[108:111]
	v_mfma_f32_16x16x32_bf16 v[104:107], v[218:221], v[178:181], v[104:107]
	v_mfma_f32_16x16x32_bf16 v[100:103], v[218:221], v[182:185], v[100:103]
	v_mfma_f32_16x16x32_bf16 v[96:99], v[218:221], v[186:189], v[96:99]
	ds_read_b128 v[242:245], v168
	ds_read_b128 v[190:193], v162 offset:33792
	s_waitcnt lgkmcnt(6)
	v_mfma_f32_16x16x32_bf16 v[92:95], v[222:225], v[174:177], v[92:95]
	v_mfma_f32_16x16x32_bf16 v[88:91], v[222:225], v[178:181], v[88:91]
	v_mfma_f32_16x16x32_bf16 v[84:87], v[222:225], v[182:185], v[84:87]
	v_mfma_f32_16x16x32_bf16 v[80:83], v[222:225], v[186:189], v[80:83]
	ds_read_b128 v[214:217], v170 offset:1024
	ds_read_b128 v[194:197], v162 offset:35840
	s_waitcnt lgkmcnt(7)
	v_mfma_f32_16x16x32_bf16 v[76:79], v[226:229], v[174:177], v[76:79]
	v_mfma_f32_16x16x32_bf16 v[72:75], v[226:229], v[178:181], v[72:75]
	v_mfma_f32_16x16x32_bf16 v[68:71], v[226:229], v[182:185], v[68:71]
	v_mfma_f32_16x16x32_bf16 v[64:67], v[226:229], v[186:189], v[64:67]
	ds_read_b128 v[218:221], v171 offset:1024
	ds_read_b128 v[198:201], v162 offset:37888
	s_waitcnt lgkmcnt(8)
	v_mfma_f32_16x16x32_bf16 v[60:63], v[230:233], v[174:177], v[60:63]
	v_mfma_f32_16x16x32_bf16 v[56:59], v[230:233], v[178:181], v[56:59]
	v_mfma_f32_16x16x32_bf16 v[52:55], v[230:233], v[182:185], v[52:55]
	v_mfma_f32_16x16x32_bf16 v[48:51], v[230:233], v[186:189], v[48:51]
	ds_read_b128 v[222:225], v163 offset:1024
	ds_read_b128 v[210:213], v162 offset:39936
	s_waitcnt lgkmcnt(9)
	v_mfma_f32_16x16x32_bf16 v[44:47], v[234:237], v[174:177], v[44:47]
	v_mfma_f32_16x16x32_bf16 v[40:43], v[234:237], v[178:181], v[40:43]
	v_mfma_f32_16x16x32_bf16 v[36:39], v[234:237], v[182:185], v[36:39]
	v_mfma_f32_16x16x32_bf16 v[32:35], v[234:237], v[186:189], v[32:35]
	ds_read_b128 v[226:229], v164 offset:1024
	s_waitcnt lgkmcnt(9)
	v_mfma_f32_16x16x32_bf16 v[28:31], v[238:241], v[174:177], v[28:31]
	v_mfma_f32_16x16x32_bf16 v[24:27], v[238:241], v[178:181], v[24:27]
	v_mfma_f32_16x16x32_bf16 v[20:23], v[238:241], v[182:185], v[20:23]
	v_mfma_f32_16x16x32_bf16 v[16:19], v[238:241], v[186:189], v[16:19]
	ds_read_b128 v[230:233], v165 offset:1024
	s_waitcnt lgkmcnt(9)
	v_mfma_f32_16x16x32_bf16 v[12:15], v[242:245], v[174:177], v[12:15]
	v_mfma_f32_16x16x32_bf16 v[8:11], v[242:245], v[178:181], v[8:11]
	v_mfma_f32_16x16x32_bf16 v[4:7], v[242:245], v[182:185], v[4:7]
	v_mfma_f32_16x16x32_bf16 v[0:3], v[242:245], v[186:189], v[0:3]
	ds_read_b128 v[234:237], v166 offset:1024
	s_waitcnt lgkmcnt(3)
	v_mfma_f32_16x16x32_bf16 v[124:127], v[214:217], v[190:193], v[124:127]
	v_mfma_f32_16x16x32_bf16 v[120:123], v[214:217], v[194:197], v[120:123]
	v_mfma_f32_16x16x32_bf16 v[116:119], v[214:217], v[198:201], v[116:119]
	v_mfma_f32_16x16x32_bf16 v[112:115], v[214:217], v[210:213], v[112:115]
	ds_read_b128 v[238:241], v167 offset:1024
	v_mfma_f32_16x16x32_bf16 v[108:111], v[218:221], v[190:193], v[108:111]
	v_mfma_f32_16x16x32_bf16 v[104:107], v[218:221], v[194:197], v[104:107]
	v_mfma_f32_16x16x32_bf16 v[100:103], v[218:221], v[198:201], v[100:103]
	v_mfma_f32_16x16x32_bf16 v[96:99], v[218:221], v[210:213], v[96:99]
	ds_read_b128 v[242:245], v168 offset:1024
	v_mfma_f32_16x16x32_bf16 v[92:95], v[222:225], v[190:193], v[92:95]
	v_mfma_f32_16x16x32_bf16 v[88:91], v[222:225], v[194:197], v[88:91]
	v_mfma_f32_16x16x32_bf16 v[84:87], v[222:225], v[198:201], v[84:87]
	v_mfma_f32_16x16x32_bf16 v[80:83], v[222:225], v[210:213], v[80:83]
	s_waitcnt lgkmcnt(4)
	v_mfma_f32_16x16x32_bf16 v[76:79], v[226:229], v[190:193], v[76:79]
	v_mfma_f32_16x16x32_bf16 v[72:75], v[226:229], v[194:197], v[72:75]
	v_mfma_f32_16x16x32_bf16 v[68:71], v[226:229], v[198:201], v[68:71]
	v_mfma_f32_16x16x32_bf16 v[64:67], v[226:229], v[210:213], v[64:67]
	s_waitcnt lgkmcnt(3)
	v_mfma_f32_16x16x32_bf16 v[60:63], v[230:233], v[190:193], v[60:63]
	v_mfma_f32_16x16x32_bf16 v[56:59], v[230:233], v[194:197], v[56:59]
	v_mfma_f32_16x16x32_bf16 v[52:55], v[230:233], v[198:201], v[52:55]
	v_mfma_f32_16x16x32_bf16 v[48:51], v[230:233], v[210:213], v[48:51]
	s_waitcnt lgkmcnt(0)
	s_waitcnt vmcnt(0)
	s_barrier
	s_cmp_gt_u32 s23, 13
	s_cbranch_scc1 .Lg1_last
	ds_read_b128 v[174:177], v153 offset:32768
	ds_read_b128 v[178:181], v153 offset:34816
	ds_read_b128 v[182:185], v153 offset:36864
	ds_read_b128 v[186:189], v153 offset:38912
	ds_read_b128 v[214:217], v154
	ds_read_b128 v[218:221], v155
	ds_read_b128 v[222:225], v156
	s_add_u32 m0, s24, 0x10400
	v_mfma_f32_16x16x32_bf16 v[44:47], v[234:237], v[190:193], v[44:47]
	global_load_lds_dwordx4 v246, s[98:99]
	s_add_u32 m0, s24, 0x12400
	v_mfma_f32_16x16x32_bf16 v[40:43], v[234:237], v[194:197], v[40:43]
	global_load_lds_dwordx4 v247, s[98:99]
	s_add_u32 m0, s24, 0x14400
	v_mfma_f32_16x16x32_bf16 v[36:39], v[234:237], v[198:201], v[36:39]
	global_load_lds_dwordx4 v248, s[98:99]
	s_add_u32 m0, s24, 0x16400
	v_mfma_f32_16x16x32_bf16 v[32:35], v[234:237], v[210:213], v[32:35]
	global_load_lds_dwordx4 v249, s[98:99]
	s_add_u32 m0, s24, 0x18400
	v_mfma_f32_16x16x32_bf16 v[28:31], v[238:241], v[190:193], v[28:31]
	global_load_lds_dwordx4 v246, s[100:101]
	s_add_u32 m0, s24, 0x1a400
	v_mfma_f32_16x16x32_bf16 v[24:27], v[238:241], v[194:197], v[24:27]
	global_load_lds_dwordx4 v247, s[100:101]
	s_add_u32 m0, s24, 0x1c400
	v_mfma_f32_16x16x32_bf16 v[20:23], v[238:241], v[198:201], v[20:23]
	global_load_lds_dwordx4 v248, s[100:101]
	s_add_u32 m0, s24, 0x1e400
	v_mfma_f32_16x16x32_bf16 v[16:19], v[238:241], v[210:213], v[16:19]
	global_load_lds_dwordx4 v249, s[100:101]
	v_mfma_f32_16x16x32_bf16 v[12:15], v[242:245], v[190:193], v[12:15]
	v_mfma_f32_16x16x32_bf16 v[8:11], v[242:245], v[194:197], v[8:11]
	v_mfma_f32_16x16x32_bf16 v[4:7], v[242:245], v[198:201], v[4:7]
	v_mfma_f32_16x16x32_bf16 v[0:3], v[242:245], v[210:213], v[0:3]
	s_add_u32 s98, s98, 0x80
	s_addc_u32 s99, s99, 0
	s_add_u32 s100, s100, 0x80
	s_addc_u32 s101, s101, 0
	s_add_i32 s23, s23, 2
	s_branch .LBB0_203

.LBB0_1788:
	ds_read_b128 v[222:225], v159
	ds_read_b128 v[226:229], v160
	ds_read_b128 v[230:233], v161
	s_waitcnt lgkmcnt(5)
	v_mfma_f32_16x16x32_bf16 v[124:127], v[210:213], v[178:181], v[124:127]
	v_mfma_f32_16x16x32_bf16 v[120:123], v[210:213], v[182:185], v[120:123]
	v_mfma_f32_16x16x32_bf16 v[116:119], v[210:213], v[186:189], v[116:119]
	v_mfma_f32_16x16x32_bf16 v[112:115], v[210:213], v[190:193], v[112:115]
	ds_read_b128 v[234:237], v162
	s_waitcnt lgkmcnt(5)
	v_mfma_f32_16x16x32_bf16 v[108:111], v[214:217], v[178:181], v[108:111]
	v_mfma_f32_16x16x32_bf16 v[104:107], v[214:217], v[182:185], v[104:107]
	v_mfma_f32_16x16x32_bf16 v[100:103], v[214:217], v[186:189], v[100:103]
	v_mfma_f32_16x16x32_bf16 v[96:99], v[214:217], v[190:193], v[96:99]
	ds_read_b128 v[238:241], v163
	ds_read_b128 v[194:197], v155 offset:33792
	s_waitcnt lgkmcnt(6)
	v_mfma_f32_16x16x32_bf16 v[92:95], v[218:221], v[178:181], v[92:95]
	v_mfma_f32_16x16x32_bf16 v[88:91], v[218:221], v[182:185], v[88:91]
	v_mfma_f32_16x16x32_bf16 v[84:87], v[218:221], v[186:189], v[84:87]
	v_mfma_f32_16x16x32_bf16 v[80:83], v[218:221], v[190:193], v[80:83]
	ds_read_b128 v[210:213], v156 offset:1024
	ds_read_b128 v[198:201], v155 offset:35840
	s_waitcnt lgkmcnt(7)
	v_mfma_f32_16x16x32_bf16 v[76:79], v[222:225], v[178:181], v[76:79]
	v_mfma_f32_16x16x32_bf16 v[72:75], v[222:225], v[182:185], v[72:75]
	v_mfma_f32_16x16x32_bf16 v[68:71], v[222:225], v[186:189], v[68:71]
	v_mfma_f32_16x16x32_bf16 v[64:67], v[222:225], v[190:193], v[64:67]
	ds_read_b128 v[214:217], v157 offset:1024
	ds_read_b128 v[202:205], v155 offset:37888
	s_waitcnt lgkmcnt(8)
	v_mfma_f32_16x16x32_bf16 v[60:63], v[226:229], v[178:181], v[60:63]
	v_mfma_f32_16x16x32_bf16 v[56:59], v[226:229], v[182:185], v[56:59]
	v_mfma_f32_16x16x32_bf16 v[52:55], v[226:229], v[186:189], v[52:55]
	v_mfma_f32_16x16x32_bf16 v[48:51], v[226:229], v[190:193], v[48:51]
	ds_read_b128 v[218:221], v158 offset:1024
	ds_read_b128 v[206:209], v155 offset:39936
	s_waitcnt lgkmcnt(9)
	v_mfma_f32_16x16x32_bf16 v[44:47], v[230:233], v[178:181], v[44:47]
	v_mfma_f32_16x16x32_bf16 v[40:43], v[230:233], v[182:185], v[40:43]
	v_mfma_f32_16x16x32_bf16 v[36:39], v[230:233], v[186:189], v[36:39]
	v_mfma_f32_16x16x32_bf16 v[32:35], v[230:233], v[190:193], v[32:35]
	ds_read_b128 v[222:225], v159 offset:1024
	s_waitcnt lgkmcnt(9)
	v_mfma_f32_16x16x32_bf16 v[28:31], v[234:237], v[178:181], v[28:31]
	v_mfma_f32_16x16x32_bf16 v[24:27], v[234:237], v[182:185], v[24:27]
	v_mfma_f32_16x16x32_bf16 v[20:23], v[234:237], v[186:189], v[20:23]
	v_mfma_f32_16x16x32_bf16 v[16:19], v[234:237], v[190:193], v[16:19]
	ds_read_b128 v[226:229], v160 offset:1024
	s_waitcnt lgkmcnt(9)
	v_mfma_f32_16x16x32_bf16 v[12:15], v[238:241], v[178:181], v[12:15]
	v_mfma_f32_16x16x32_bf16 v[8:11], v[238:241], v[182:185], v[8:11]
	v_mfma_f32_16x16x32_bf16 v[4:7], v[238:241], v[186:189], v[4:7]
	v_mfma_f32_16x16x32_bf16 v[0:3], v[238:241], v[190:193], v[0:3]
	ds_read_b128 v[230:233], v161 offset:1024
	s_waitcnt lgkmcnt(3)
	v_mfma_f32_16x16x32_bf16 v[124:127], v[210:213], v[194:197], v[124:127]
	v_mfma_f32_16x16x32_bf16 v[120:123], v[210:213], v[198:201], v[120:123]
	v_mfma_f32_16x16x32_bf16 v[116:119], v[210:213], v[202:205], v[116:119]
	v_mfma_f32_16x16x32_bf16 v[112:115], v[210:213], v[206:209], v[112:115]
	ds_read_b128 v[234:237], v162 offset:1024
	v_mfma_f32_16x16x32_bf16 v[108:111], v[214:217], v[194:197], v[108:111]
	v_mfma_f32_16x16x32_bf16 v[104:107], v[214:217], v[198:201], v[104:107]
	v_mfma_f32_16x16x32_bf16 v[100:103], v[214:217], v[202:205], v[100:103]
	v_mfma_f32_16x16x32_bf16 v[96:99], v[214:217], v[206:209], v[96:99]
	ds_read_b128 v[238:241], v163 offset:1024
	v_mfma_f32_16x16x32_bf16 v[92:95], v[218:221], v[194:197], v[92:95]
	v_mfma_f32_16x16x32_bf16 v[88:91], v[218:221], v[198:201], v[88:91]
	v_mfma_f32_16x16x32_bf16 v[84:87], v[218:221], v[202:205], v[84:87]
	v_mfma_f32_16x16x32_bf16 v[80:83], v[218:221], v[206:209], v[80:83]
	s_waitcnt lgkmcnt(4)
	v_mfma_f32_16x16x32_bf16 v[76:79], v[222:225], v[194:197], v[76:79]
	v_mfma_f32_16x16x32_bf16 v[72:75], v[222:225], v[198:201], v[72:75]
	v_mfma_f32_16x16x32_bf16 v[68:71], v[222:225], v[202:205], v[68:71]
	v_mfma_f32_16x16x32_bf16 v[64:67], v[222:225], v[206:209], v[64:67]
	s_waitcnt lgkmcnt(3)
	v_mfma_f32_16x16x32_bf16 v[60:63], v[226:229], v[194:197], v[60:63]
	v_mfma_f32_16x16x32_bf16 v[56:59], v[226:229], v[198:201], v[56:59]
	v_mfma_f32_16x16x32_bf16 v[52:55], v[226:229], v[202:205], v[52:55]
	v_mfma_f32_16x16x32_bf16 v[48:51], v[226:229], v[206:209], v[48:51]
	s_waitcnt lgkmcnt(0)
	s_waitcnt vmcnt(0)
	s_barrier
	ds_read_b128 v[178:181], v164 offset:32768
	ds_read_b128 v[182:185], v164 offset:34816
	ds_read_b128 v[186:189], v164 offset:36864
	ds_read_b128 v[190:193], v164 offset:38912
	ds_read_b128 v[210:213], v172
	ds_read_b128 v[214:217], v173
	ds_read_b128 v[218:221], v165
	s_cmp_gt_u32 s1, 13
	s_cbranch_scc1 .Lg4_nostage0
	s_add_u32 m0, s45, 0x0
	v_mfma_f32_16x16x32_bf16 v[44:47], v[230:233], v[194:197], v[44:47]
	global_load_lds_dwordx4 v174, s[98:99]
	s_add_u32 m0, s45, 0x2000
	v_mfma_f32_16x16x32_bf16 v[40:43], v[230:233], v[198:201], v[40:43]
	global_load_lds_dwordx4 v175, s[98:99]
	s_add_u32 m0, s45, 0x4000
	v_mfma_f32_16x16x32_bf16 v[36:39], v[230:233], v[202:205], v[36:39]
	global_load_lds_dwordx4 v176, s[98:99]
	s_add_u32 m0, s45, 0x6000
	v_mfma_f32_16x16x32_bf16 v[32:35], v[230:233], v[206:209], v[32:35]
	global_load_lds_dwordx4 v177, s[98:99]
	s_add_u32 m0, s45, 0x8000
	v_mfma_f32_16x16x32_bf16 v[28:31], v[234:237], v[194:197], v[28:31]
	global_load_lds_dwordx4 v174, s[100:101]
	s_add_u32 m0, s45, 0xa000
	v_mfma_f32_16x16x32_bf16 v[24:27], v[234:237], v[198:201], v[24:27]
	global_load_lds_dwordx4 v175, s[100:101]
	s_add_u32 m0, s45, 0xc000
	v_mfma_f32_16x16x32_bf16 v[20:23], v[234:237], v[202:205], v[20:23]
	global_load_lds_dwordx4 v176, s[100:101]
	s_add_u32 m0, s45, 0xe000
	v_mfma_f32_16x16x32_bf16 v[16:19], v[234:237], v[206:209], v[16:19]
	global_load_lds_dwordx4 v177, s[100:101]
	v_mfma_f32_16x16x32_bf16 v[12:15], v[238:241], v[194:197], v[12:15]
	v_mfma_f32_16x16x32_bf16 v[8:11], v[238:241], v[198:201], v[8:11]
	v_mfma_f32_16x16x32_bf16 v[4:7], v[238:241], v[202:205], v[4:7]
	v_mfma_f32_16x16x32_bf16 v[0:3], v[238:241], v[206:209], v[0:3]
	s_add_u32 s98, s98, 0x80
	s_addc_u32 s99, s99, 0
	s_add_u32 s100, s100, 0x80
	s_addc_u32 s101, s101, 0
	s_branch .Lg4_half1

.Lg4_half1:
	ds_read_b128 v[222:225], v166
	ds_read_b128 v[226:229], v167
	ds_read_b128 v[230:233], v168
	s_waitcnt lgkmcnt(5)
	v_mfma_f32_16x16x32_bf16 v[124:127], v[210:213], v[178:181], v[124:127]
	v_mfma_f32_16x16x32_bf16 v[120:123], v[210:213], v[182:185], v[120:123]
	v_mfma_f32_16x16x32_bf16 v[116:119], v[210:213], v[186:189], v[116:119]
	v_mfma_f32_16x16x32_bf16 v[112:115], v[210:213], v[190:193], v[112:115]
	ds_read_b128 v[234:237], v169
	s_waitcnt lgkmcnt(5)
	v_mfma_f32_16x16x32_bf16 v[108:111], v[214:217], v[178:181], v[108:111]
	v_mfma_f32_16x16x32_bf16 v[104:107], v[214:217], v[182:185], v[104:107]
	v_mfma_f32_16x16x32_bf16 v[100:103], v[214:217], v[186:189], v[100:103]
	v_mfma_f32_16x16x32_bf16 v[96:99], v[214:217], v[190:193], v[96:99]
	ds_read_b128 v[238:241], v170
	ds_read_b128 v[194:197], v164 offset:33792
	s_waitcnt lgkmcnt(6)
	v_mfma_f32_16x16x32_bf16 v[92:95], v[218:221], v[178:181], v[92:95]
	v_mfma_f32_16x16x32_bf16 v[88:91], v[218:221], v[182:185], v[88:91]
	v_mfma_f32_16x16x32_bf16 v[84:87], v[218:221], v[186:189], v[84:87]
	v_mfma_f32_16x16x32_bf16 v[80:83], v[218:221], v[190:193], v[80:83]
	ds_read_b128 v[210:213], v172 offset:1024
	ds_read_b128 v[198:201], v164 offset:35840
	s_waitcnt lgkmcnt(7)
	v_mfma_f32_16x16x32_bf16 v[76:79], v[222:225], v[178:181], v[76:79]
	v_mfma_f32_16x16x32_bf16 v[72:75], v[222:225], v[182:185], v[72:75]
	v_mfma_f32_16x16x32_bf16 v[68:71], v[222:225], v[186:189], v[68:71]
	v_mfma_f32_16x16x32_bf16 v[64:67], v[222:225], v[190:193], v[64:67]
	ds_read_b128 v[214:217], v173 offset:1024
	ds_read_b128 v[202:205], v164 offset:37888
	s_waitcnt lgkmcnt(8)
	v_mfma_f32_16x16x32_bf16 v[60:63], v[226:229], v[178:181], v[60:63]
	v_mfma_f32_16x16x32_bf16 v[56:59], v[226:229], v[182:185], v[56:59]
	v_mfma_f32_16x16x32_bf16 v[52:55], v[226:229], v[186:189], v[52:55]
	v_mfma_f32_16x16x32_bf16 v[48:51], v[226:229], v[190:193], v[48:51]
	ds_read_b128 v[218:221], v165 offset:1024
	ds_read_b128 v[206:209], v164 offset:39936
	s_waitcnt lgkmcnt(9)
	v_mfma_f32_16x16x32_bf16 v[44:47], v[230:233], v[178:181], v[44:47]
	v_mfma_f32_16x16x32_bf16 v[40:43], v[230:233], v[182:185], v[40:43]
	v_mfma_f32_16x16x32_bf16 v[36:39], v[230:233], v[186:189], v[36:39]
	v_mfma_f32_16x16x32_bf16 v[32:35], v[230:233], v[190:193], v[32:35]
	ds_read_b128 v[222:225], v166 offset:1024
	s_waitcnt lgkmcnt(9)
	v_mfma_f32_16x16x32_bf16 v[28:31], v[234:237], v[178:181], v[28:31]
	v_mfma_f32_16x16x32_bf16 v[24:27], v[234:237], v[182:185], v[24:27]
	v_mfma_f32_16x16x32_bf16 v[20:23], v[234:237], v[186:189], v[20:23]
	v_mfma_f32_16x16x32_bf16 v[16:19], v[234:237], v[190:193], v[16:19]
	ds_read_b128 v[226:229], v167 offset:1024
	s_waitcnt lgkmcnt(9)
	v_mfma_f32_16x16x32_bf16 v[12:15], v[238:241], v[178:181], v[12:15]
	v_mfma_f32_16x16x32_bf16 v[8:11], v[238:241], v[182:185], v[8:11]
	v_mfma_f32_16x16x32_bf16 v[4:7], v[238:241], v[186:189], v[4:7]
	v_mfma_f32_16x16x32_bf16 v[0:3], v[238:241], v[190:193], v[0:3]
	ds_read_b128 v[230:233], v168 offset:1024
	s_waitcnt lgkmcnt(3)
	v_mfma_f32_16x16x32_bf16 v[124:127], v[210:213], v[194:197], v[124:127]
	v_mfma_f32_16x16x32_bf16 v[120:123], v[210:213], v[198:201], v[120:123]
	v_mfma_f32_16x16x32_bf16 v[116:119], v[210:213], v[202:205], v[116:119]
	v_mfma_f32_16x16x32_bf16 v[112:115], v[210:213], v[206:209], v[112:115]
	ds_read_b128 v[234:237], v169 offset:1024
	v_mfma_f32_16x16x32_bf16 v[108:111], v[214:217], v[194:197], v[108:111]
	v_mfma_f32_16x16x32_bf16 v[104:107], v[214:217], v[198:201], v[104:107]
	v_mfma_f32_16x16x32_bf16 v[100:103], v[214:217], v[202:205], v[100:103]
	v_mfma_f32_16x16x32_bf16 v[96:99], v[214:217], v[206:209], v[96:99]
	ds_read_b128 v[238:241], v170 offset:1024
	v_mfma_f32_16x16x32_bf16 v[92:95], v[218:221], v[194:197], v[92:95]
	v_mfma_f32_16x16x32_bf16 v[88:91], v[218:221], v[198:201], v[88:91]
	v_mfma_f32_16x16x32_bf16 v[84:87], v[218:221], v[202:205], v[84:87]
	v_mfma_f32_16x16x32_bf16 v[80:83], v[218:221], v[206:209], v[80:83]
	s_waitcnt lgkmcnt(4)
	v_mfma_f32_16x16x32_bf16 v[76:79], v[222:225], v[194:197], v[76:79]
	v_mfma_f32_16x16x32_bf16 v[72:75], v[222:225], v[198:201], v[72:75]
	v_mfma_f32_16x16x32_bf16 v[68:71], v[222:225], v[202:205], v[68:71]
	v_mfma_f32_16x16x32_bf16 v[64:67], v[222:225], v[206:209], v[64:67]
	s_waitcnt lgkmcnt(3)
	v_mfma_f32_16x16x32_bf16 v[60:63], v[226:229], v[194:197], v[60:63]
	v_mfma_f32_16x16x32_bf16 v[56:59], v[226:229], v[198:201], v[56:59]
	v_mfma_f32_16x16x32_bf16 v[52:55], v[226:229], v[202:205], v[52:55]
	v_mfma_f32_16x16x32_bf16 v[48:51], v[226:229], v[206:209], v[48:51]
	s_waitcnt lgkmcnt(0)
	s_waitcnt vmcnt(0)
	s_barrier
	s_cmp_gt_u32 s1, 13
	s_cbranch_scc1 .Lg4_last
	ds_read_b128 v[178:181], v155 offset:32768
	ds_read_b128 v[182:185], v155 offset:34816
	ds_read_b128 v[186:189], v155 offset:36864
	ds_read_b128 v[190:193], v155 offset:38912
	ds_read_b128 v[210:213], v156
	ds_read_b128 v[214:217], v157
	ds_read_b128 v[218:221], v158
	s_add_u32 m0, s45, 0x10400
	v_mfma_f32_16x16x32_bf16 v[44:47], v[230:233], v[194:197], v[44:47]
	global_load_lds_dwordx4 v174, s[98:99]
	s_add_u32 m0, s45, 0x12400
	v_mfma_f32_16x16x32_bf16 v[40:43], v[230:233], v[198:201], v[40:43]
	global_load_lds_dwordx4 v175, s[98:99]
	s_add_u32 m0, s45, 0x14400
	v_mfma_f32_16x16x32_bf16 v[36:39], v[230:233], v[202:205], v[36:39]
	global_load_lds_dwordx4 v176, s[98:99]
	s_add_u32 m0, s45, 0x16400
	v_mfma_f32_16x16x32_bf16 v[32:35], v[230:233], v[206:209], v[32:35]
	global_load_lds_dwordx4 v177, s[98:99]
	s_add_u32 m0, s45, 0x18400
	v_mfma_f32_16x16x32_bf16 v[28:31], v[234:237], v[194:197], v[28:31]
	global_load_lds_dwordx4 v174, s[100:101]
	s_add_u32 m0, s45, 0x1a400
	v_mfma_f32_16x16x32_bf16 v[24:27], v[234:237], v[198:201], v[24:27]
	global_load_lds_dwordx4 v175, s[100:101]
	s_add_u32 m0, s45, 0x1c400
	v_mfma_f32_16x16x32_bf16 v[20:23], v[234:237], v[202:205], v[20:23]
	global_load_lds_dwordx4 v176, s[100:101]
	s_add_u32 m0, s45, 0x1e400
	v_mfma_f32_16x16x32_bf16 v[16:19], v[234:237], v[206:209], v[16:19]
	global_load_lds_dwordx4 v177, s[100:101]
	v_mfma_f32_16x16x32_bf16 v[12:15], v[238:241], v[194:197], v[12:15]
	v_mfma_f32_16x16x32_bf16 v[8:11], v[238:241], v[198:201], v[8:11]
	v_mfma_f32_16x16x32_bf16 v[4:7], v[238:241], v[202:205], v[4:7]
	v_mfma_f32_16x16x32_bf16 v[0:3], v[238:241], v[206:209], v[0:3]
	s_add_u32 s98, s98, 0x80
	s_addc_u32 s99, s99, 0
	s_add_u32 s100, s100, 0x80
	s_addc_u32 s101, s101, 0
	s_add_i32 s1, s1, 2
	s_branch .LBB0_1788
